# ret_m1: rope cos/sin rows of token blocks 1-3 also prefetched with block 0 (rounds 1-3 no longer wait on memory)
# baseline (speedup 1.0000x reference)
; #define LAS __attribute__((address_space(3)))
; __device__ __forceinline__ void ld8bf(const bf16_t* p, float (&o)[8]) { unpack8(*(const u32x4*)p, o); }
; __device__ __forceinline__ float ret_lg(int h) { return log1pf(-exp2f(-5.0f - (float)h)); }
; __device__ __forceinline__ void w_ret_m1(unsigned char* ws, const bf16_t* proj, LAS unsigned char* wl, int b, int ck_, int h, int lane) {
;     LAS bf16_t* vT = (LAS bf16_t*)wl; LAS bf16_t* kT = (LAS bf16_t*)(wl + TILE_B);
;     const int row0 = b * SEQ + 64 * ck_, lo = lane & 15, fq = lane >> 4; const float lg = ret_lg(h);
;     const float* cosT = (const float*)(ws + WS_ROPE); const float* sinT = cosT + SEQ * 32;
; #pragma unroll
;     for (int i = 0; i < 4; ++i) { const int m = (lane >> 2) + 16 * i, cp = lane & 3; float x1[8], x2[8];
;         const bf16_t* src = proj + (size_t)(row0 + m) * NIN + C_RK + 64 * h; ld8bf(src + 8 * cp, x1); ld8bf(src + 32 + 8 * cp, x2);
;         const float* cp_ = cosT + (64 * ck_ + m) * 32 + 8 * cp; const float* sp_ = sinT + (64 * ck_ + m) * 32 + 8 * cp;
;         const float sc = 0.125f * __expf((float)(63 - m) * lg);
.LBB0_516:
	s_lshr_b32 s21, s20, 8
	s_lshr_b32 s24, s20, 9
	s_add_i32 s21, s21, s20
	s_and_b32 s24, s24, 12
	s_add_i32 s21, s21, s24
	s_and_b32 s24, s21, 12
	s_cmp_lg_u32 s24, 8
	s_cbranch_scc1 .LBB0_515
	s_and_b32 s34, s21, 11
	s_ashr_i32 s21, s20, 31
	s_ashr_i32 s24, s20, 4
	s_lshr_b32 s21, s21, 25
	s_add_i32 s34, s34, -8
	s_add_i32 s27, s24, s21
	v_cvt_f32_u32_e32 v0, s34
	s_ashr_i32 s21, s27, 7
	s_and_b32 s27, s27, 0xffffff80
	s_sub_i32 s27, s24, s27
	s_lshl_b32 s24, s21, 13
	s_lshl_b32 s38, s27, 6
	s_add_i32 s35, s38, s24
	v_sub_f32_e32 v0, 0xc0a00000, v0
	s_mov_b32 s24, 0xc2fc0000
	v_cmp_gt_f32_e32 vcc, s24, v0
	s_and_b64 s[40:41], vcc, exec
	s_cselect_b32 s24, 0xffffffc0, 0
	v_cndmask_b32_e32 v1, 0, v204, vcc
	v_add_f32_e32 v0, v0, v1
	v_exp_f32_e32 v0, v0
	v_mov_b32_e32 v25, v144
	v_mov_b64_e32 v[22:23], s[8:9]
	v_ldexp_f32 v2, v0, s24
	v_sub_f32_e32 v4, 1.0, v2
	v_add_f32_e32 v0, -1.0, v4
	v_sub_f32_e32 v1, v0, v4
	v_add_f32_e32 v1, 1.0, v1
	v_sub_f32_e64 v0, -v2, v0
	v_add_f32_e32 v5, v0, v1
	v_frexp_mant_f32_e32 v0, v4
	v_cmp_gt_f32_e32 vcc, s77, v0
	v_cvt_f64_f32_e32 v[0:1], v4
	v_frexp_exp_i32_f64_e32 v0, v[0:1]
	v_subbrev_co_u32_e32 v10, vcc, 0, v0, vcc
	v_sub_u32_e32 v0, 0, v10
	v_ldexp_f32 v1, v4, v0
	v_add_f32_e32 v4, -1.0, v1
	v_add_f32_e32 v6, 1.0, v1
	v_ldexp_f32 v0, v5, v0
	v_add_f32_e32 v5, 1.0, v4
	v_add_f32_e32 v7, -1.0, v6
	v_sub_f32_e32 v5, v1, v5
	v_sub_f32_e32 v1, v1, v7
	v_add_f32_e32 v5, v0, v5
	v_add_f32_e32 v0, v0, v1
	v_add_f32_e32 v11, v6, v0
	v_rcp_f32_e32 v13, v11
	v_sub_f32_e32 v1, v11, v6
	v_sub_f32_e32 v12, v0, v1
	v_add_f32_e32 v1, v4, v5
	v_mul_f32_e32 v15, v1, v13
	v_sub_f32_e32 v0, v1, v4
	v_mul_f32_e32 v4, v11, v15
	v_fma_f32 v6, v15, v11, -v4
	v_fmac_f32_e32 v6, v15, v12
	v_sub_f32_e32 v14, v5, v0
	v_add_f32_e32 v0, v4, v6
	v_sub_f32_e32 v5, v1, v0
	v_pk_add_f32 v[8:9], v[0:1], v[4:5] neg_lo:[0,1] neg_hi:[0,1]
	v_mov_b32_e32 v7, v0
	v_pk_add_f32 v[0:1], v[8:9], v[6:7] neg_lo:[0,1] neg_hi:[0,1]
	v_cmp_nlt_f32_e32 vcc, 1.0, v2
	v_add_f32_e32 v1, v14, v1
	v_add_f32_e32 v0, v0, v1
	v_add_f32_e32 v1, v5, v0
	v_mul_f32_e32 v14, v13, v1
	v_mul_f32_e32 v4, v11, v14
	v_fma_f32 v6, v14, v11, -v4
	v_fmac_f32_e32 v6, v14, v12
	v_sub_f32_e32 v5, v5, v1
	v_add_f32_e32 v11, v0, v5
	v_add_f32_e32 v0, v4, v6
	v_sub_f32_e32 v5, v1, v0
	v_pk_add_f32 v[8:9], v[0:1], v[4:5] neg_lo:[0,1] neg_hi:[0,1]
	v_mov_b32_e32 v7, v0
	v_pk_add_f32 v[0:1], v[8:9], v[6:7] neg_lo:[0,1] neg_hi:[0,1]
	v_ashrrev_i32_e32 v36, 2, v25
	v_add_f32_e32 v1, v11, v1
	v_add_f32_e32 v0, v0, v1
	v_add_f32_e32 v1, v15, v14
	v_add_f32_e32 v0, v5, v0
	v_sub_f32_e32 v4, v1, v15
	v_mul_f32_e32 v0, v13, v0
	v_sub_f32_e32 v4, v14, v4
	v_add_f32_e32 v4, v4, v0
	v_add_f32_e32 v6, v1, v4
	v_mul_f32_e32 v7, v6, v6
	v_fmamk_f32 v0, v7, 0x3e9b6dac, v201
	v_fmaak_f32 v169, v7, v0, 0x3f2aaada
	v_cvt_f32_i32_e32 v0, v10
	v_sub_f32_e32 v1, v6, v1
	v_sub_f32_e32 v1, v4, v1
	v_ldexp_f32 v8, v1, 1
	v_mul_f32_e32 v1, v6, v7
	v_ldexp_f32 v5, v6, 1
	v_pk_mul_f32 v[6:7], v[0:1], v[168:169]
	s_lshl_b32 s24, s34, 7
	v_fma_f32 v4, v0, s94, -v6
	v_fmac_f32_e32 v4, 0xb102e308, v0
	v_pk_add_f32 v[0:1], v[6:7], v[4:5]
	s_nop 0
	v_sub_f32_e32 v5, v1, v5
	v_sub_f32_e32 v5, v7, v5
	v_add_f32_e32 v9, v8, v5
	v_mov_b32_e32 v8, v6
	v_pk_add_f32 v[6:7], v[0:1], v[6:7] neg_lo:[0,1] neg_hi:[0,1]
	v_pk_add_f32 v[10:11], v[0:1], v[8:9]
	v_mov_b32_e32 v5, v0
	v_mov_b32_e32 v7, v11
	v_pk_add_f32 v[12:13], v[4:5], v[6:7] neg_lo:[0,1] neg_hi:[0,1]
	v_pk_add_f32 v[4:5], v[4:5], v[6:7]
	v_mov_b32_e32 v16, v1
	v_pk_add_f32 v[6:7], v[4:5], v[0:1] op_sel:[1,0] op_sel_hi:[0,1] neg_lo:[0,1] neg_hi:[0,1]
	v_pk_add_f32 v[14:15], v[10:11], v[6:7] op_sel_hi:[1,0] neg_lo:[0,1] neg_hi:[0,1]
	v_mov_b32_e32 v10, v11
	v_mov_b32_e32 v11, v5
	v_mov_b32_e32 v17, v6
	v_pk_add_f32 v[6:7], v[10:11], v[16:17] neg_lo:[0,1] neg_hi:[0,1]
	v_mov_b32_e32 v8, v9
	v_mov_b32_e32 v9, v0
	v_pk_add_f32 v[0:1], v[8:9], v[6:7] neg_lo:[0,1] neg_hi:[0,1]
	v_mov_b32_e32 v14, v12
	v_pk_add_f32 v[6:7], v[14:15], v[0:1]
	v_mov_b32_e32 v13, v5
	v_pk_add_f32 v[8:9], v[6:7], v[6:7] op_sel:[0,1] op_sel_hi:[1,0]
	s_nop 0
	v_pk_add_f32 v[4:5], v[4:5], v[8:9] op_sel:[1,0] op_sel_hi:[0,1]
	v_mov_b32_e32 v7, v4
	v_pk_add_f32 v[10:11], v[6:7], v[12:13] neg_lo:[0,1] neg_hi:[0,1]
	v_mov_b32_e32 v1, v8
	v_sub_f32_e32 v5, v6, v10
	v_pk_add_f32 v[0:1], v[0:1], v[10:11] neg_lo:[0,1] neg_hi:[0,1]
	v_sub_f32_e32 v5, v12, v5
	v_add_f32_e32 v0, v0, v5
	v_add_f32_e32 v0, v0, v1
	v_add_f32_e32 v0, v4, v0
	v_cndmask_b32_e32 v0, v205, v0, vcc
	v_cmp_neq_f32_e32 vcc, 1.0, v2
	v_add_lshl_u32 v12, v36, s38, 5
	v_ashrrev_i32_e32 v13, 31, v12
	v_cndmask_b32_e32 v0, v206, v0, vcc
	v_cmp_gt_f32_e32 vcc, s95, v2
	v_lshlrev_b64 v[12:13], 2, v[12:13]
	s_nop 0
	v_cndmask_b32_e64 v35, v0, -v2, vcc
	v_lshlrev_b32_e32 v0, 3, v25
	v_and_b32_e32 v34, 24, v0
	v_lshlrev_b32_e32 v2, 2, v34
	v_lshl_add_u64 v[0:1], s[4:5], 0, v[2:3]
	v_lshl_add_u64 v[20:21], s[82:83], 0, v[2:3]
	v_lshl_add_u64 v[18:19], v[0:1], 0, v[12:13]
	v_lshl_add_u64 v[16:17], v[20:21], 0, v[12:13]
	v_sub_u32_e32 v12, 63, v36
	v_cvt_f32_i32_e32 v12, v12
	v_add_u32_e32 v2, s35, v36
	v_mad_i64_i32 v[4:5], s[40:41], v2, s72, v[22:23]
	v_mul_f32_e32 v12, v35, v12
	v_mul_f32_e32 v12, 0x3fb8aa3b, v12
	v_exp_f32_e32 v12, v12
	v_lshl_add_u64 v[4:5], v[4:5], 0, s[24:25]
	v_lshlrev_b32_e32 v2, 1, v34
	v_lshl_add_u64 v[4:5], v[4:5], 0, v[2:3]
	v_mov_b32_e32 v124, 0x18000
	v_mov_b32_e32 v125, 0
	v_lshl_add_u64 v[126:127], v[4:5], 0, v[124:125]
	global_load_dwordx4 v[8:11], v[4:5], off offset:2560
	s_nop 0
	global_load_dwordx4 v[4:7], v[4:5], off offset:2624
	v_mul_f32_e32 v24, 0x3e000000, v12
; #define LAS __attribute__((address_space(3)))
; __device__ __forceinline__ u32x4 pack8(const float (&v)[8]) { u32x4 w; w.x = pk2(v[0], v[1]); w.y = pk2(v[2], v[3]); w.z = pk2(v[4], v[5]); w.w = pk2(v[6], v[7]); return w; }
; __device__ __forceinline__ void ld8bf(const bf16_t* p, float (&o)[8]) { unpack8(*(const u32x4*)p, o); }
; __device__ __forceinline__ void w_ret_m1(unsigned char* ws, const bf16_t* proj, LAS unsigned char* wl, int b, int ck_, int h, int lane) {
;     ...
;     for (int i = 0; i < 4; ++i) { const int m = (lane >> 2) + 16 * i, cp = lane & 3; float x1[8], x2[8];
;         const bf16_t* src = proj + (size_t)(row0 + m) * NIN + C_RK + 64 * h; ld8bf(src + 8 * cp, x1); ld8bf(src + 32 + 8 * cp, x2);
;         const float* cp_ = cosT + (64 * ck_ + m) * 32 + 8 * cp; const float* sp_ = sinT + (64 * ck_ + m) * 32 + 8 * cp;
;         const float sc = 0.125f * __expf((float)(63 - m) * lg);
;         float o1[8], o2[8];
; #pragma unroll
;         for (int j = 0; j < 8; ++j) { const float cs = cp_[j], sn = sp_[j]; o1[j] = (x1[j] * cs - x2[j] * sn) * sc; o2[j] = (x2[j] * cs + x1[j] * sn) * sc; }
;         *(LAS u32x4*)(kT + m * LD + 8 * cp) = pack8(o1); *(LAS u32x4*)(kT + m * LD + 32 + 8 * cp) = pack8(o2); }
	global_load_dwordx4 v[12:15], v[18:19], off
	global_load_dwordx4 v[28:31], v[16:17], off
	global_load_dwordx4 v[178:181], v[18:19], off offset:16
	global_load_dwordx4 v[182:185], v[16:17], off offset:16
	global_load_dwordx4 v[100:103], v[126:127], off offset:2560
	global_load_dwordx4 v[104:107], v[126:127], off offset:2624
	v_lshl_add_u64 v[126:127], v[126:127], 0, v[124:125]
	global_load_dwordx4 v[108:111], v[126:127], off offset:2560
	global_load_dwordx4 v[112:115], v[126:127], off offset:2624
	v_lshl_add_u64 v[126:127], v[126:127], 0, v[124:125]
	global_load_dwordx4 v[116:119], v[126:127], off offset:2560
	global_load_dwordx4 v[120:123], v[126:127], off offset:2624
	v_mov_b32_e32 v130, 0x800
	v_mov_b32_e32 v131, 0
	v_lshl_add_u64 v[128:129], v[18:19], 0, v[130:131]
	v_lshl_add_u64 v[132:133], v[16:17], 0, v[130:131]
	global_load_dwordx4 v[46:49], v[128:129], off
	global_load_dwordx4 v[50:53], v[132:133], off
	global_load_dwordx4 v[54:57], v[128:129], off offset:16
	global_load_dwordx4 v[58:61], v[132:133], off offset:16
	v_lshl_add_u64 v[128:129], v[128:129], 0, v[130:131]
	v_lshl_add_u64 v[132:133], v[132:133], 0, v[130:131]
	global_load_dwordx4 v[62:65], v[128:129], off
	global_load_dwordx4 v[66:69], v[132:133], off
	global_load_dwordx4 v[70:73], v[128:129], off offset:16
	global_load_dwordx4 v[74:77], v[132:133], off offset:16
	v_lshl_add_u64 v[128:129], v[128:129], 0, v[130:131]
	v_lshl_add_u64 v[132:133], v[132:133], 0, v[130:131]
	global_load_dwordx4 v[78:81], v[128:129], off
	global_load_dwordx4 v[82:85], v[132:133], off
	global_load_dwordx4 v[86:89], v[128:129], off offset:16
	global_load_dwordx4 v[90:93], v[132:133], off offset:16
	s_waitcnt vmcnt(0) lgkmcnt(0)
	v_lshlrev_b32_e32 v32, 16, v8
	v_and_b32_e32 v33, 0xffff0000, v8
	v_lshlrev_b32_e32 v38, 16, v4
	v_and_b32_e32 v39, 0xffff0000, v4
	v_pk_mul_f32 v[26:27], v[28:29], v[32:33]
	v_pk_mul_f32 v[28:29], v[28:29], v[38:39]
	v_pk_fma_f32 v[26:27], v[12:13], v[38:39], v[26:27]
	v_pk_fma_f32 v[12:13], v[12:13], v[32:33], v[28:29] neg_lo:[0,0,1] neg_hi:[0,0,1]
	v_lshlrev_b32_e32 v8, 16, v9
	v_and_b32_e32 v9, 0xffff0000, v9
	v_pk_mul_f32 v[28:29], v[24:25], v[12:13] op_sel_hi:[0,1]
	v_lshlrev_b32_e32 v12, 16, v5
	v_and_b32_e32 v13, 0xffff0000, v5
	v_pk_mul_f32 v[4:5], v[30:31], v[8:9]
	v_lshlrev_b32_e32 v32, 16, v6
	v_pk_fma_f32 v[4:5], v[14:15], v[12:13], v[4:5]
	v_pk_mul_f32 v[12:13], v[30:31], v[12:13]
	v_lshlrev_b32_e32 v30, 16, v10
	v_pk_fma_f32 v[8:9], v[14:15], v[8:9], v[12:13] neg_lo:[0,0,1] neg_hi:[0,0,1]
	v_mov_b64_e32 v[12:13], v[178:179]
	v_mov_b64_e32 v[14:15], v[180:181]
	s_nop 0
	v_mov_b64_e32 v[16:17], v[182:183]
	v_mov_b64_e32 v[18:19], v[184:185]
	v_and_b32_e32 v31, 0xffff0000, v10
	v_and_b32_e32 v33, 0xffff0000, v6
	v_lshlrev_b32_e32 v10, 16, v11
	v_and_b32_e32 v11, 0xffff0000, v11
	v_lshlrev_b32_e32 v6, 16, v7
	v_and_b32_e32 v7, 0xffff0000, v7
	v_pk_mul_f32 v[8:9], v[24:25], v[8:9] op_sel_hi:[0,1]
	v_pk_mul_f32 v[4:5], v[24:25], v[4:5] op_sel_hi:[0,1]
	v_pk_mul_f32 v[26:27], v[24:25], v[26:27] op_sel_hi:[0,1]
	s_waitcnt vmcnt(0) lgkmcnt(0)
	v_pk_mul_f32 v[38:39], v[16:17], v[30:31]
	v_pk_mul_f32 v[16:17], v[16:17], v[32:33]
	v_pk_fma_f32 v[38:39], v[12:13], v[32:33], v[38:39]
	v_pk_fma_f32 v[12:13], v[12:13], v[30:31], v[16:17] neg_lo:[0,0,1] neg_hi:[0,0,1]
	v_pk_mul_f32 v[16:17], v[18:19], v[10:11]
	v_pk_mul_f32 v[12:13], v[24:25], v[12:13] op_sel_hi:[0,1]
	v_pk_fma_f32 v[16:17], v[14:15], v[6:7], v[16:17]
	v_pk_mul_f32 v[6:7], v[18:19], v[6:7]
	v_pk_mul_f32 v[38:39], v[24:25], v[38:39] op_sel_hi:[0,1]
	v_pk_fma_f32 v[6:7], v[14:15], v[10:11], v[6:7] neg_lo:[0,0,1] neg_hi:[0,0,1]
	v_pk_mul_f32 v[16:17], v[24:25], v[16:17] op_sel_hi:[0,1]
	v_pk_mul_f32 v[10:11], v[24:25], v[6:7] op_sel_hi:[0,1]
	v_cvt_pk_bf16_f32 v7, v8, v9
	v_cvt_pk_bf16_f32 v9, v10, v11
	v_mul_lo_u32 v10, v36, s23
	v_cvt_pk_bf16_f32 v6, v28, v29
	v_cvt_pk_bf16_f32 v8, v12, v13
	v_add3_u32 v18, s6, v10, v2
	v_add_u32_e32 v12, 16, v36
	ds_write_b128 v18, v[6:9] offset:9216
	v_cvt_pk_bf16_f32 v7, v4, v5
	v_add_u32_e32 v4, s35, v12
	v_mad_i64_i32 v[4:5], s[40:41], v4, s72, v[22:23]
	v_add_lshl_u32 v12, v12, s38, 5
	v_cvt_pk_bf16_f32 v6, v26, v27
	v_cvt_pk_bf16_f32 v8, v38, v39
	v_cvt_pk_bf16_f32 v9, v16, v17
	v_lshl_add_u64 v[4:5], v[4:5], 0, s[24:25]
	v_ashrrev_i32_e32 v13, 31, v12
	ds_write_b128 v18, v[6:9] offset:9280
	v_lshl_add_u64 v[4:5], v[4:5], 0, v[2:3]
	v_lshlrev_b64 v[12:13], 2, v[12:13]
	v_mov_b64_e32 v[8:9], v[100:101]
	v_mov_b64_e32 v[10:11], v[102:103]
	s_nop 0
	v_mov_b64_e32 v[4:5], v[104:105]
	v_mov_b64_e32 v[6:7], v[106:107]
	v_lshl_add_u64 v[38:39], v[0:1], 0, v[12:13]
	v_lshl_add_u64 v[40:41], v[20:21], 0, v[12:13]
	v_mov_b64_e32 v[26:27], v[46:47]
	v_mov_b64_e32 v[28:29], v[48:49]
	v_mov_b64_e32 v[30:31], v[50:51]
	v_mov_b64_e32 v[32:33], v[52:53]
	v_mov_b64_e32 v[178:179], v[54:55]
	v_mov_b64_e32 v[180:181], v[56:57]
	v_mov_b64_e32 v[182:183], v[58:59]
	v_mov_b64_e32 v[184:185], v[60:61]
	v_sub_u32_e32 v12, 47, v36
	v_cvt_f32_i32_e32 v12, v12
	v_mul_f32_e32 v12, v35, v12
	v_mul_f32_e32 v12, 0x3fb8aa3b, v12
	v_exp_f32_e32 v12, v12
	s_waitcnt vmcnt(0) lgkmcnt(0)
; #define LAS __attribute__((address_space(3)))
; __device__ __forceinline__ u32x4 pack8(const float (&v)[8]) { u32x4 w; w.x = pk2(v[0], v[1]); w.y = pk2(v[2], v[3]); w.z = pk2(v[4], v[5]); w.w = pk2(v[6], v[7]); return w; }
; __device__ __forceinline__ void ld8bf(const bf16_t* p, float (&o)[8]) { unpack8(*(const u32x4*)p, o); }
; __device__ __forceinline__ void w_ret_m1(unsigned char* ws, const bf16_t* proj, LAS unsigned char* wl, int b, int ck_, int h, int lane) {
;     ...
;     for (int i = 0; i < 4; ++i) { const int m = (lane >> 2) + 16 * i, cp = lane & 3; float x1[8], x2[8];
;         const bf16_t* src = proj + (size_t)(row0 + m) * NIN + C_RK + 64 * h; ld8bf(src + 8 * cp, x1); ld8bf(src + 32 + 8 * cp, x2);
;         const float* cp_ = cosT + (64 * ck_ + m) * 32 + 8 * cp; const float* sp_ = sinT + (64 * ck_ + m) * 32 + 8 * cp;
;         const float sc = 0.125f * __expf((float)(63 - m) * lg);
;         float o1[8], o2[8];
; #pragma unroll
;         for (int j = 0; j < 8; ++j) { const float cs = cp_[j], sn = sp_[j]; o1[j] = (x1[j] * cs - x2[j] * sn) * sc; o2[j] = (x2[j] * cs + x1[j] * sn) * sc; }
;         *(LAS u32x4*)(kT + m * LD + 8 * cp) = pack8(o1); *(LAS u32x4*)(kT + m * LD + 32 + 8 * cp) = pack8(o2); }
	v_lshlrev_b32_e32 v16, 16, v8
	v_and_b32_e32 v17, 0xffff0000, v8
	v_lshlrev_b32_e32 v42, 16, v4
	v_and_b32_e32 v43, 0xffff0000, v4
	v_pk_mul_f32 v[14:15], v[30:31], v[16:17]
	v_pk_mul_f32 v[30:31], v[30:31], v[42:43]
	v_lshlrev_b32_e32 v8, 16, v9
	v_and_b32_e32 v9, 0xffff0000, v9
	v_pk_fma_f32 v[14:15], v[26:27], v[42:43], v[14:15]
	v_pk_fma_f32 v[16:17], v[26:27], v[16:17], v[30:31] neg_lo:[0,0,1] neg_hi:[0,0,1]
	v_lshlrev_b32_e32 v26, 16, v5
	v_and_b32_e32 v27, 0xffff0000, v5
	v_pk_mul_f32 v[4:5], v[32:33], v[8:9]
	v_lshlrev_b32_e32 v42, 16, v10
	v_pk_fma_f32 v[4:5], v[28:29], v[26:27], v[4:5]
	v_pk_mul_f32 v[26:27], v[32:33], v[26:27]
	v_and_b32_e32 v43, 0xffff0000, v10
	v_pk_fma_f32 v[8:9], v[28:29], v[8:9], v[26:27] neg_lo:[0,0,1] neg_hi:[0,0,1]
	v_mov_b64_e32 v[26:27], v[178:179]
	v_mov_b64_e32 v[28:29], v[180:181]
	v_mov_b64_e32 v[30:31], v[182:183]
	v_mov_b64_e32 v[32:33], v[184:185]
	v_lshlrev_b32_e32 v44, 16, v6
	v_and_b32_e32 v45, 0xffff0000, v6
	v_lshlrev_b32_e32 v10, 16, v11
	v_and_b32_e32 v11, 0xffff0000, v11
	v_lshlrev_b32_e32 v6, 16, v7
	v_and_b32_e32 v7, 0xffff0000, v7
	v_mul_f32_e32 v12, 0x3e000000, v12
	v_pk_mul_f32 v[16:17], v[12:13], v[16:17] op_sel_hi:[0,1]
	v_pk_mul_f32 v[8:9], v[12:13], v[8:9] op_sel_hi:[0,1]
	v_pk_mul_f32 v[14:15], v[12:13], v[14:15] op_sel_hi:[0,1]
	v_pk_mul_f32 v[4:5], v[12:13], v[4:5] op_sel_hi:[0,1]
	s_waitcnt vmcnt(0) lgkmcnt(0)
	v_pk_mul_f32 v[38:39], v[30:31], v[42:43]
	v_pk_mul_f32 v[30:31], v[30:31], v[44:45]
	v_pk_fma_f32 v[38:39], v[26:27], v[44:45], v[38:39]
	v_pk_fma_f32 v[26:27], v[26:27], v[42:43], v[30:31] neg_lo:[0,0,1] neg_hi:[0,0,1]
	v_pk_mul_f32 v[30:31], v[32:33], v[10:11]
	v_pk_mul_f32 v[26:27], v[12:13], v[26:27] op_sel_hi:[0,1]
	v_pk_fma_f32 v[30:31], v[28:29], v[6:7], v[30:31]
	v_pk_mul_f32 v[6:7], v[32:33], v[6:7]
	v_pk_mul_f32 v[38:39], v[12:13], v[38:39] op_sel_hi:[0,1]
	v_pk_fma_f32 v[6:7], v[28:29], v[10:11], v[6:7] neg_lo:[0,0,1] neg_hi:[0,0,1]
	v_pk_mul_f32 v[30:31], v[12:13], v[30:31] op_sel_hi:[0,1]
	v_pk_mul_f32 v[10:11], v[12:13], v[6:7] op_sel_hi:[0,1]
	v_cvt_pk_bf16_f32 v6, v16, v17
	v_cvt_pk_bf16_f32 v7, v8, v9
	v_cvt_pk_bf16_f32 v8, v26, v27
	v_cvt_pk_bf16_f32 v9, v10, v11
	v_add_u32_e32 v12, 32, v36
	ds_write_b128 v18, v[6:9] offset:11520
	v_cvt_pk_bf16_f32 v7, v4, v5
	v_add_u32_e32 v4, s35, v12
	v_mad_i64_i32 v[4:5], s[40:41], v4, s72, v[22:23]
	v_add_lshl_u32 v12, v12, s38, 5
	v_cvt_pk_bf16_f32 v6, v14, v15
	v_cvt_pk_bf16_f32 v8, v38, v39
	v_cvt_pk_bf16_f32 v9, v30, v31
	v_lshl_add_u64 v[4:5], v[4:5], 0, s[24:25]
	v_ashrrev_i32_e32 v13, 31, v12
	ds_write_b128 v18, v[6:9] offset:11584
	v_lshl_add_u64 v[4:5], v[4:5], 0, v[2:3]
	v_lshlrev_b64 v[12:13], 2, v[12:13]
	v_mov_b64_e32 v[8:9], v[108:109]
	v_mov_b64_e32 v[10:11], v[110:111]
	s_nop 0
	v_mov_b64_e32 v[4:5], v[112:113]
	v_mov_b64_e32 v[6:7], v[114:115]
	v_lshl_add_u64 v[38:39], v[0:1], 0, v[12:13]
	v_lshl_add_u64 v[40:41], v[20:21], 0, v[12:13]
	v_mov_b64_e32 v[26:27], v[62:63]
	v_mov_b64_e32 v[28:29], v[64:65]
	v_mov_b64_e32 v[30:31], v[66:67]
	v_mov_b64_e32 v[32:33], v[68:69]
	v_mov_b64_e32 v[178:179], v[70:71]
	v_mov_b64_e32 v[180:181], v[72:73]
	v_mov_b64_e32 v[182:183], v[74:75]
	v_mov_b64_e32 v[184:185], v[76:77]
	v_sub_u32_e32 v12, 31, v36
	v_cvt_f32_i32_e32 v12, v12
	v_mul_f32_e32 v12, v35, v12
	v_mul_f32_e32 v12, 0x3fb8aa3b, v12
	v_exp_f32_e32 v12, v12
	s_waitcnt vmcnt(0) lgkmcnt(0)
	v_lshlrev_b32_e32 v16, 16, v8
	v_and_b32_e32 v17, 0xffff0000, v8
	v_lshlrev_b32_e32 v42, 16, v4
	v_and_b32_e32 v43, 0xffff0000, v4
	v_pk_mul_f32 v[14:15], v[30:31], v[16:17]
	v_pk_mul_f32 v[30:31], v[30:31], v[42:43]
	v_lshlrev_b32_e32 v8, 16, v9
	v_and_b32_e32 v9, 0xffff0000, v9
	v_pk_fma_f32 v[14:15], v[26:27], v[42:43], v[14:15]
	v_pk_fma_f32 v[16:17], v[26:27], v[16:17], v[30:31] neg_lo:[0,0,1] neg_hi:[0,0,1]
	v_lshlrev_b32_e32 v26, 16, v5
	v_and_b32_e32 v27, 0xffff0000, v5
	v_pk_mul_f32 v[4:5], v[32:33], v[8:9]
	v_lshlrev_b32_e32 v42, 16, v10
	v_pk_fma_f32 v[4:5], v[28:29], v[26:27], v[4:5]
	v_pk_mul_f32 v[26:27], v[32:33], v[26:27]
	v_and_b32_e32 v43, 0xffff0000, v10
	v_pk_fma_f32 v[8:9], v[28:29], v[8:9], v[26:27] neg_lo:[0,0,1] neg_hi:[0,0,1]
	v_mov_b64_e32 v[26:27], v[178:179]
	v_mov_b64_e32 v[28:29], v[180:181]
	v_mov_b64_e32 v[30:31], v[182:183]
	v_mov_b64_e32 v[32:33], v[184:185]
	v_lshlrev_b32_e32 v44, 16, v6
	v_and_b32_e32 v45, 0xffff0000, v6
	v_lshlrev_b32_e32 v10, 16, v11
	v_and_b32_e32 v11, 0xffff0000, v11
	v_lshlrev_b32_e32 v6, 16, v7
	v_and_b32_e32 v7, 0xffff0000, v7
	v_mul_f32_e32 v12, 0x3e000000, v12
	v_pk_mul_f32 v[16:17], v[12:13], v[16:17] op_sel_hi:[0,1]
	v_pk_mul_f32 v[8:9], v[12:13], v[8:9] op_sel_hi:[0,1]
	v_pk_mul_f32 v[14:15], v[12:13], v[14:15] op_sel_hi:[0,1]
	v_pk_mul_f32 v[4:5], v[12:13], v[4:5] op_sel_hi:[0,1]
	s_waitcnt vmcnt(0) lgkmcnt(0)
; #define LAS __attribute__((address_space(3)))
; __device__ __forceinline__ u32x4 pack8(const float (&v)[8]) { u32x4 w; w.x = pk2(v[0], v[1]); w.y = pk2(v[2], v[3]); w.z = pk2(v[4], v[5]); w.w = pk2(v[6], v[7]); return w; }
; __device__ __forceinline__ void ld8bf(const bf16_t* p, float (&o)[8]) { unpack8(*(const u32x4*)p, o); }
; __device__ __forceinline__ void w_ret_m1(unsigned char* ws, const bf16_t* proj, LAS unsigned char* wl, int b, int ck_, int h, int lane) {
;     ...
;     for (int i = 0; i < 4; ++i) { const int m = (lane >> 2) + 16 * i, cp = lane & 3; float x1[8], x2[8];
;         const bf16_t* src = proj + (size_t)(row0 + m) * NIN + C_RK + 64 * h; ld8bf(src + 8 * cp, x1); ld8bf(src + 32 + 8 * cp, x2);
;         const float* cp_ = cosT + (64 * ck_ + m) * 32 + 8 * cp; const float* sp_ = sinT + (64 * ck_ + m) * 32 + 8 * cp;
;         const float sc = 0.125f * __expf((float)(63 - m) * lg);
;         float o1[8], o2[8];
; #pragma unroll
;         for (int j = 0; j < 8; ++j) { const float cs = cp_[j], sn = sp_[j]; o1[j] = (x1[j] * cs - x2[j] * sn) * sc; o2[j] = (x2[j] * cs + x1[j] * sn) * sc; }
;         *(LAS u32x4*)(kT + m * LD + 8 * cp) = pack8(o1); *(LAS u32x4*)(kT + m * LD + 32 + 8 * cp) = pack8(o2); }
;     w_store_vT(vT, proj + (size_t)row0 * NIN + C_RV + 64 * h, lane);
	v_pk_mul_f32 v[38:39], v[30:31], v[42:43]
	v_pk_mul_f32 v[30:31], v[30:31], v[44:45]
	v_pk_fma_f32 v[38:39], v[26:27], v[44:45], v[38:39]
	v_pk_fma_f32 v[26:27], v[26:27], v[42:43], v[30:31] neg_lo:[0,0,1] neg_hi:[0,0,1]
	v_pk_mul_f32 v[30:31], v[32:33], v[10:11]
	v_pk_mul_f32 v[26:27], v[12:13], v[26:27] op_sel_hi:[0,1]
	v_pk_fma_f32 v[30:31], v[28:29], v[6:7], v[30:31]
	v_pk_mul_f32 v[6:7], v[32:33], v[6:7]
	v_pk_mul_f32 v[38:39], v[12:13], v[38:39] op_sel_hi:[0,1]
	v_pk_fma_f32 v[6:7], v[28:29], v[10:11], v[6:7] neg_lo:[0,0,1] neg_hi:[0,0,1]
	v_pk_mul_f32 v[30:31], v[12:13], v[30:31] op_sel_hi:[0,1]
	v_pk_mul_f32 v[10:11], v[12:13], v[6:7] op_sel_hi:[0,1]
	v_cvt_pk_bf16_f32 v6, v16, v17
	v_cvt_pk_bf16_f32 v7, v8, v9
	v_cvt_pk_bf16_f32 v8, v26, v27
	v_cvt_pk_bf16_f32 v9, v10, v11
	v_add_u32_e32 v12, 48, v36
	ds_write_b128 v18, v[6:9] offset:13824
	v_cvt_pk_bf16_f32 v7, v4, v5
	v_add_u32_e32 v4, s35, v12
	v_mad_i64_i32 v[4:5], s[40:41], v4, s72, v[22:23]
	v_add_lshl_u32 v12, v12, s38, 5
	v_cvt_pk_bf16_f32 v6, v14, v15
	v_cvt_pk_bf16_f32 v8, v38, v39
	v_cvt_pk_bf16_f32 v9, v30, v31
	v_lshl_add_u64 v[4:5], v[4:5], 0, s[24:25]
	v_ashrrev_i32_e32 v13, 31, v12
	ds_write_b128 v18, v[6:9] offset:13888
	v_lshl_add_u64 v[4:5], v[4:5], 0, v[2:3]
	v_lshlrev_b64 v[12:13], 2, v[12:13]
	v_mov_b64_e32 v[8:9], v[116:117]
	v_mov_b64_e32 v[10:11], v[118:119]
	s_nop 0
	v_mov_b64_e32 v[4:5], v[120:121]
	v_mov_b64_e32 v[6:7], v[122:123]
	v_lshl_add_u64 v[26:27], v[0:1], 0, v[12:13]
	v_lshl_add_u64 v[28:29], v[20:21], 0, v[12:13]
	v_mov_b64_e32 v[14:15], v[78:79]
	v_mov_b64_e32 v[16:17], v[80:81]
	v_mov_b64_e32 v[20:21], v[82:83]
	v_mov_b64_e32 v[22:23], v[84:85]
	v_mov_b64_e32 v[178:179], v[86:87]
	v_mov_b64_e32 v[180:181], v[88:89]
	v_mov_b64_e32 v[182:183], v[90:91]
	v_mov_b64_e32 v[184:185], v[92:93]
	v_sub_u32_e32 v0, 15, v36
	v_cvt_f32_i32_e32 v0, v0
	s_mul_hi_i32 s38, s35, 0x1800
	s_mulk_i32 s35, 0x1800
	s_add_u32 s35, s8, s35
	v_mul_f32_e32 v0, v35, v0
	v_mul_f32_e32 v0, 0x3fb8aa3b, v0
	v_exp_f32_e32 v0, v0
	s_addc_u32 s39, s9, s38
	s_add_u32 s38, s35, s24
	s_addc_u32 s39, s39, 0
	v_mul_f32_e32 v0, 0x3e000000, v0
	s_lshl_b32 s21, s21, 9
	s_lshl_b32 s24, s27, 2
	s_add_i32 s24, s24, s21
	s_or_b32 s34, s34, s24
	s_ashr_i32 s35, s34, 31
	s_lshl_b64 s[34:35], s[34:35], 13
	s_add_u32 s34, s67, s34
	s_addc_u32 s35, s28, s35
	s_waitcnt vmcnt(0) lgkmcnt(0)
	v_lshlrev_b32_e32 v30, 16, v8
	v_and_b32_e32 v31, 0xffff0000, v8
	v_lshlrev_b32_e32 v32, 16, v4
	v_and_b32_e32 v33, 0xffff0000, v4
	v_pk_mul_f32 v[12:13], v[20:21], v[30:31]
	v_pk_mul_f32 v[20:21], v[20:21], v[32:33]
	v_lshlrev_b32_e32 v8, 16, v9
	v_and_b32_e32 v9, 0xffff0000, v9
	v_pk_fma_f32 v[12:13], v[14:15], v[32:33], v[12:13]
	v_pk_fma_f32 v[14:15], v[14:15], v[30:31], v[20:21] neg_lo:[0,0,1] neg_hi:[0,0,1]
	v_lshlrev_b32_e32 v20, 16, v5
	v_and_b32_e32 v21, 0xffff0000, v5
	v_pk_mul_f32 v[4:5], v[22:23], v[8:9]
	v_lshlrev_b32_e32 v30, 16, v6
	v_pk_fma_f32 v[4:5], v[16:17], v[20:21], v[4:5]
	v_pk_mul_f32 v[20:21], v[22:23], v[20:21]
	v_and_b32_e32 v31, 0xffff0000, v6
	v_pk_fma_f32 v[8:9], v[16:17], v[8:9], v[20:21] neg_lo:[0,0,1] neg_hi:[0,0,1]
	v_mov_b64_e32 v[20:21], v[178:179]
	v_mov_b64_e32 v[22:23], v[180:181]
	s_nop 0
	v_mov_b64_e32 v[26:27], v[182:183]
	v_mov_b64_e32 v[28:29], v[184:185]
	v_lshlrev_b32_e32 v16, 16, v10
	v_and_b32_e32 v17, 0xffff0000, v10
	v_lshlrev_b32_e32 v10, 16, v11
	v_and_b32_e32 v11, 0xffff0000, v11
	v_lshlrev_b32_e32 v6, 16, v7
	v_and_b32_e32 v7, 0xffff0000, v7
	v_pk_mul_f32 v[12:13], v[0:1], v[12:13] op_sel_hi:[0,1]
	v_pk_mul_f32 v[14:15], v[0:1], v[14:15] op_sel_hi:[0,1]
	v_pk_mul_f32 v[4:5], v[0:1], v[4:5] op_sel_hi:[0,1]
	v_pk_mul_f32 v[8:9], v[0:1], v[8:9] op_sel_hi:[0,1]
	s_waitcnt vmcnt(0) lgkmcnt(0)
	v_pk_mul_f32 v[32:33], v[26:27], v[16:17]
	v_pk_mul_f32 v[26:27], v[26:27], v[30:31]
	v_pk_fma_f32 v[32:33], v[20:21], v[30:31], v[32:33]
	v_pk_fma_f32 v[16:17], v[20:21], v[16:17], v[26:27] neg_lo:[0,0,1] neg_hi:[0,0,1]
	v_pk_mul_f32 v[20:21], v[28:29], v[10:11]
	v_pk_mul_f32 v[32:33], v[0:1], v[32:33] op_sel_hi:[0,1]
	v_pk_fma_f32 v[20:21], v[22:23], v[6:7], v[20:21]
	v_pk_mul_f32 v[6:7], v[28:29], v[6:7]
	v_pk_mul_f32 v[16:17], v[0:1], v[16:17] op_sel_hi:[0,1]
	v_pk_fma_f32 v[6:7], v[22:23], v[10:11], v[6:7] neg_lo:[0,0,1] neg_hi:[0,0,1]
	v_pk_mul_f32 v[20:21], v[0:1], v[20:21] op_sel_hi:[0,1]
	v_pk_mul_f32 v[0:1], v[0:1], v[6:7] op_sel_hi:[0,1]
	v_cvt_pk_bf16_f32 v6, v14, v15
	v_cvt_pk_bf16_f32 v7, v8, v9
	v_cvt_pk_bf16_f32 v8, v16, v17
	v_cvt_pk_bf16_f32 v9, v0, v1
	v_lshlrev_b32_e32 v0, 4, v25
	ds_write_b128 v18, v[6:9] offset:16128
	v_cvt_pk_bf16_f32 v6, v12, v13
	v_cvt_pk_bf16_f32 v7, v4, v5
	v_cvt_pk_bf16_f32 v8, v32, v33
	v_cvt_pk_bf16_f32 v9, v20, v21
	v_and_b32_e32 v2, 0x70, v0
	ds_write_b128 v18, v[6:9] offset:16192
	v_ashrrev_i32_e32 v9, 3, v25
	v_lshl_add_u64 v[0:1], s[38:39], 0, v[2:3]
	v_mad_i64_i32 v[4:5], s[38:39], v9, s72, v[0:1]
	global_load_dwordx4 v[224:227], v[4:5], off offset:3072
	v_add_u32_e32 v4, 8, v9
	v_mad_i64_i32 v[4:5], s[38:39], v4, s72, v[0:1]
	global_load_dwordx4 v[228:231], v[4:5], off offset:3072
	v_add_u32_e32 v4, 16, v9
	v_mad_i64_i32 v[4:5], s[38:39], v4, s72, v[0:1]
	global_load_dwordx4 v[232:235], v[4:5], off offset:3072
	v_add_u32_e32 v4, 24, v9
	v_mad_i64_i32 v[4:5], s[38:39], v4, s72, v[0:1]
	global_load_dwordx4 v[236:239], v[4:5], off offset:3072
	v_add_u32_e32 v4, 32, v9
	v_mad_i64_i32 v[4:5], s[38:39], v4, s72, v[0:1]
	global_load_dwordx4 v[240:243], v[4:5], off offset:3072
	v_add_u32_e32 v4, 40, v9
	v_mad_i64_i32 v[4:5], s[38:39], v4, s72, v[0:1]
	global_load_dwordx4 v[244:247], v[4:5], off offset:3072
	v_add_u32_e32 v4, 48, v9
	v_mad_i64_i32 v[4:5], s[38:39], v4, s72, v[0:1]
	global_load_dwordx4 v[248:251], v[4:5], off offset:3072
	v_add_u32_e32 v4, 56, v9
	v_mad_i64_i32 v[0:1], s[38:39], v4, s72, v[0:1]
	global_load_dwordx4 v[186:189], v[0:1], off offset:3072
	v_mul_lo_u32 v10, v9, s23
	v_add3_u32 v2, s6, v2, v10
	v_ashrrev_i32_e32 v8, 4, v25
	v_and_b32_e32 v17, 15, v25
	v_lshlrev_b32_e32 v0, 2, v8
	v_ashrrev_i32_e32 v1, 31, v0
	v_lshl_add_u64 v[0:1], v[0:1], 1, s[34:35]
	v_lshl_add_u64 v[26:27], v[0:1], 0, 32
	s_mov_b64 s[34:35], 0x60
	s_waitcnt vmcnt(0) lgkmcnt(0)
; #define LAS __attribute__((address_space(3)))
; __device__ __forceinline__ unsigned pk2(float lo, float hi) { const f32x2_t v = {lo, hi}; const bf16x2_t b = __builtin_convertvector(v, bf16x2_t); return __builtin_bit_cast(unsigned, b); }
; __device__ __forceinline__ void w_store_vT(LAS bf16_t* vN, const bf16_t* src, int lane) {
;     ...
;     for (int i = 0; i < 8; ++i) { const int m = (lane >> 3) + 8 * i, e0 = 8 * (lane & 7); *(LAS u32x4*)(vN + m * LD + e0) = *(const u32x4*)(src + (size_t)m * NIN + e0); }
; }
; __device__ __forceinline__ void w_kv(const LAS bf16_t* vN, const LAS bf16_t* kN, bf16_t* S, int lo, int fq) {
; #pragma unroll
;     for (int db = 0; db < 4; ++db) {
;         bf16x8 kf[2];
; #pragma unroll
;         for (int kk = 0; kk < 2; ++kk) kf[kk] = tr_frag(kN, 32 * kk + 8 * fq, 32 * kk + 8 * fq + 4, 16 * db, lo);
; #pragma unroll
;         for (int eb = 0; eb < 4; ++eb) { f32x4 acc = {0.f, 0.f, 0.f, 0.f};
; #pragma unroll
;             for (int kk = 0; kk < 2; ++kk) { const bf16x8 vf = tr_frag(vN, 32 * kk + 8 * fq, 32 * kk + 8 * fq + 4, 16 * eb, lo); acc = __builtin_amdgcn_mfma_f32_16x16x32_bf16(kf[kk], vf, acc, 0, 0, 0); }
;             *(unsigned long long*)(S + (16 * eb + lo) * 64 + 16 * db + 4 * fq) = (unsigned long long)pk2(acc[0], acc[1]) | ((unsigned long long)pk2(acc[2], acc[3]) << 32); }
;     }
; }
	ds_write_b128 v2, v[224:227]
	ds_write_b128 v2, v[228:231] offset:1152
	ds_write_b128 v2, v[232:235] offset:2304
	ds_write_b128 v2, v[236:239] offset:3456
	ds_write_b128 v2, v[240:243] offset:4608
	ds_write_b128 v2, v[244:247] offset:5760
	ds_write_b128 v2, v[248:251] offset:6912
	ds_write_b128 v2, v[186:189] offset:8064
	v_bfe_u32 v2, v25, 2, 2
	v_lshl_or_b32 v2, v8, 3, v2
	v_mul_lo_u32 v2, v2, s23
	s_waitcnt lgkmcnt(0)
	v_add3_u32 v16, s6, v34, v2
	ds_read_b64_tr_b16 v[8:9], v16 offset:9216
	ds_read_b64_tr_b16 v[10:11], v16 offset:9792
	ds_read_b64_tr_b16 v[4:5], v16 offset:13824
	ds_read_b64_tr_b16 v[6:7], v16 offset:14400
	ds_read_b64_tr_b16 v[12:13], v16
	ds_read_b64_tr_b16 v[14:15], v16 offset:576
	ds_read_b64_tr_b16 v[18:19], v16 offset:4608
	ds_read_b64_tr_b16 v[20:21], v16 offset:5184
	s_waitcnt lgkmcnt(2)
	v_mfma_f32_16x16x32_bf16 v[12:15], v[8:11], v[12:15], 0
	v_lshlrev_b32_e32 v2, 7, v17
	s_waitcnt lgkmcnt(0)
	v_mfma_f32_16x16x32_bf16 v[12:15], v[4:7], v[18:21], v[12:15]
	s_nop 7
	v_cvt_pk_bf16_f32 v18, v12, v13
	v_cvt_pk_bf16_f32 v19, v14, v15
	v_lshl_add_u64 v[12:13], v[0:1], 0, v[2:3]
	flat_store_dwordx2 v[12:13], v[18:19]
	ds_read_b64_tr_b16 v[18:19], v16 offset:32
	ds_read_b64_tr_b16 v[20:21], v16 offset:608
	ds_read_b64_tr_b16 v[22:23], v16 offset:4640
	ds_read_b64_tr_b16 v[24:25], v16 offset:5216
	s_waitcnt lgkmcnt(0)
	v_mfma_f32_16x16x32_bf16 v[18:21], v[8:11], v[18:21], 0
	v_mfma_f32_16x16x32_bf16 v[18:21], v[4:7], v[22:25], v[18:21]
	s_nop 7
	v_cvt_pk_bf16_f32 v14, v18, v19
	v_cvt_pk_bf16_f32 v15, v20, v21
	flat_store_dwordx2 v[12:13], v[14:15] offset:2048
	ds_read_b64_tr_b16 v[18:19], v16 offset:64
	ds_read_b64_tr_b16 v[20:21], v16 offset:640
	ds_read_b64_tr_b16 v[22:23], v16 offset:4672
	ds_read_b64_tr_b16 v[24:25], v16 offset:5248
	s_waitcnt lgkmcnt(0)
	v_mfma_f32_16x16x32_bf16 v[18:21], v[8:11], v[18:21], 0
	v_or_b32_e32 v14, 0x1000, v2
	v_mov_b32_e32 v15, v3
	v_or_b32_e32 v2, 0x1800, v2
	v_mfma_f32_16x16x32_bf16 v[18:21], v[4:7], v[22:25], v[18:21]
	s_nop 7
	v_cvt_pk_bf16_f32 v18, v18, v19
	v_cvt_pk_bf16_f32 v19, v20, v21
	v_lshl_add_u64 v[20:21], v[0:1], 0, v[14:15]
	flat_store_dwordx2 v[20:21], v[18:19]
	ds_read_b64_tr_b16 v[18:19], v16 offset:96
	ds_read_b64_tr_b16 v[20:21], v16 offset:672
	s_waitcnt lgkmcnt(0)
	v_mfma_f32_16x16x32_bf16 v[8:11], v[8:11], v[18:21], 0
	ds_read_b64_tr_b16 v[18:19], v16 offset:4704
	ds_read_b64_tr_b16 v[20:21], v16 offset:5280
	s_waitcnt lgkmcnt(0)
	v_mfma_f32_16x16x32_bf16 v[4:7], v[4:7], v[18:21], v[8:11]
	s_nop 7
	v_cvt_pk_bf16_f32 v4, v4, v5
	v_cvt_pk_bf16_f32 v5, v6, v7
	v_lshl_add_u64 v[6:7], v[0:1], 0, v[2:3]
	flat_store_dwordx2 v[6:7], v[4:5]
	ds_read_b64_tr_b16 v[4:5], v16 offset:9248
	ds_read_b64_tr_b16 v[6:7], v16 offset:9824
	ds_read_b64_tr_b16 v[8:9], v16 offset:13856
	ds_read_b64_tr_b16 v[10:11], v16 offset:14432
	ds_read_b64_tr_b16 v[18:19], v16
	ds_read_b64_tr_b16 v[20:21], v16 offset:576
	ds_read_b64_tr_b16 v[22:23], v16 offset:4608
	ds_read_b64_tr_b16 v[24:25], v16 offset:5184
	s_waitcnt lgkmcnt(0)
	v_mfma_f32_16x16x32_bf16 v[18:21], v[4:7], v[18:21], 0
	v_mfma_f32_16x16x32_bf16 v[18:21], v[8:11], v[22:25], v[18:21]
	s_nop 7
	v_cvt_pk_bf16_f32 v18, v18, v19
	v_cvt_pk_bf16_f32 v19, v20, v21
	flat_store_dwordx2 v[12:13], v[18:19] offset:32
	ds_read_b64_tr_b16 v[18:19], v16 offset:32
	ds_read_b64_tr_b16 v[20:21], v16 offset:608
	ds_read_b64_tr_b16 v[22:23], v16 offset:4640
	ds_read_b64_tr_b16 v[24:25], v16 offset:5216
	s_waitcnt lgkmcnt(0)
	v_mfma_f32_16x16x32_bf16 v[18:21], v[4:7], v[18:21], 0
	v_mfma_f32_16x16x32_bf16 v[18:21], v[8:11], v[22:25], v[18:21]
	s_nop 7
	v_cvt_pk_bf16_f32 v18, v18, v19
	v_cvt_pk_bf16_f32 v19, v20, v21
	flat_store_dwordx2 v[12:13], v[18:19] offset:2080
	ds_read_b64_tr_b16 v[18:19], v16 offset:64
	ds_read_b64_tr_b16 v[20:21], v16 offset:640
	ds_read_b64_tr_b16 v[22:23], v16 offset:4672
	ds_read_b64_tr_b16 v[24:25], v16 offset:5248
	s_waitcnt lgkmcnt(0)
	v_mfma_f32_16x16x32_bf16 v[18:21], v[4:7], v[18:21], 0
	v_mfma_f32_16x16x32_bf16 v[18:21], v[8:11], v[22:25], v[18:21]
	s_nop 7
	v_cvt_pk_bf16_f32 v18, v18, v19
	v_cvt_pk_bf16_f32 v19, v20, v21
	v_lshl_add_u64 v[20:21], v[26:27], 0, v[14:15]
	flat_store_dwordx2 v[20:21], v[18:19]
	ds_read_b64_tr_b16 v[18:19], v16 offset:96
	ds_read_b64_tr_b16 v[20:21], v16 offset:672
	s_waitcnt lgkmcnt(0)
	v_mfma_f32_16x16x32_bf16 v[4:7], v[4:7], v[18:21], 0
	ds_read_b64_tr_b16 v[18:19], v16 offset:4704
	ds_read_b64_tr_b16 v[20:21], v16 offset:5280
	s_waitcnt lgkmcnt(0)
; #define LAS __attribute__((address_space(3)))
; __device__ __forceinline__ unsigned pk2(float lo, float hi) { const f32x2_t v = {lo, hi}; const bf16x2_t b = __builtin_convertvector(v, bf16x2_t); return __builtin_bit_cast(unsigned, b); }
; __device__ __forceinline__ void w_kv(const LAS bf16_t* vN, const LAS bf16_t* kN, bf16_t* S, int lo, int fq) {
; #pragma unroll
;     for (int db = 0; db < 4; ++db) {
;         bf16x8 kf[2];
; #pragma unroll
;         for (int kk = 0; kk < 2; ++kk) kf[kk] = tr_frag(kN, 32 * kk + 8 * fq, 32 * kk + 8 * fq + 4, 16 * db, lo);
; #pragma unroll
;         for (int eb = 0; eb < 4; ++eb) { f32x4 acc = {0.f, 0.f, 0.f, 0.f};
; #pragma unroll
;             for (int kk = 0; kk < 2; ++kk) { const bf16x8 vf = tr_frag(vN, 32 * kk + 8 * fq, 32 * kk + 8 * fq + 4, 16 * eb, lo); acc = __builtin_amdgcn_mfma_f32_16x16x32_bf16(kf[kk], vf, acc, 0, 0, 0); }
;             *(unsigned long long*)(S + (16 * eb + lo) * 64 + 16 * db + 4 * fq) = (unsigned long long)pk2(acc[0], acc[1]) | ((unsigned long long)pk2(acc[2], acc[3]) << 32); }
;     }
; }
	v_mfma_f32_16x16x32_bf16 v[4:7], v[8:11], v[18:21], v[4:7]
	s_nop 7
	v_cvt_pk_bf16_f32 v4, v4, v5
	v_cvt_pk_bf16_f32 v5, v6, v7
	v_lshl_add_u64 v[6:7], v[26:27], 0, v[2:3]
	flat_store_dwordx2 v[6:7], v[4:5]
	ds_read_b64_tr_b16 v[4:5], v16 offset:9280
	ds_read_b64_tr_b16 v[6:7], v16 offset:9856
	ds_read_b64_tr_b16 v[8:9], v16 offset:13888
	ds_read_b64_tr_b16 v[10:11], v16 offset:14464
	ds_read_b64_tr_b16 v[18:19], v16
	ds_read_b64_tr_b16 v[20:21], v16 offset:576
	ds_read_b64_tr_b16 v[22:23], v16 offset:4608
	ds_read_b64_tr_b16 v[24:25], v16 offset:5184
	s_waitcnt lgkmcnt(0)
	v_mfma_f32_16x16x32_bf16 v[18:21], v[4:7], v[18:21], 0
	v_lshl_add_u64 v[26:27], v[0:1], 0, 64
	v_lshl_add_u64 v[0:1], v[0:1], 0, s[34:35]
	v_mfma_f32_16x16x32_bf16 v[18:21], v[8:11], v[22:25], v[18:21]
	s_nop 7
	v_cvt_pk_bf16_f32 v18, v18, v19
	v_cvt_pk_bf16_f32 v19, v20, v21
	flat_store_dwordx2 v[12:13], v[18:19] offset:64
	ds_read_b64_tr_b16 v[18:19], v16 offset:32
	ds_read_b64_tr_b16 v[20:21], v16 offset:608
	ds_read_b64_tr_b16 v[22:23], v16 offset:4640
	ds_read_b64_tr_b16 v[24:25], v16 offset:5216
	s_waitcnt lgkmcnt(0)
	v_mfma_f32_16x16x32_bf16 v[18:21], v[4:7], v[18:21], 0
	v_mfma_f32_16x16x32_bf16 v[18:21], v[8:11], v[22:25], v[18:21]
	s_nop 7
	v_cvt_pk_bf16_f32 v18, v18, v19
	v_cvt_pk_bf16_f32 v19, v20, v21
	flat_store_dwordx2 v[12:13], v[18:19] offset:2112
	ds_read_b64_tr_b16 v[18:19], v16 offset:64
	ds_read_b64_tr_b16 v[20:21], v16 offset:640
	ds_read_b64_tr_b16 v[22:23], v16 offset:4672
	ds_read_b64_tr_b16 v[24:25], v16 offset:5248
	s_waitcnt lgkmcnt(0)
	v_mfma_f32_16x16x32_bf16 v[18:21], v[4:7], v[18:21], 0
	v_mfma_f32_16x16x32_bf16 v[18:21], v[8:11], v[22:25], v[18:21]
	s_nop 7
	v_cvt_pk_bf16_f32 v18, v18, v19
	v_cvt_pk_bf16_f32 v19, v20, v21
	v_lshl_add_u64 v[20:21], v[26:27], 0, v[14:15]
	flat_store_dwordx2 v[20:21], v[18:19]
	ds_read_b64_tr_b16 v[18:19], v16 offset:96
	ds_read_b64_tr_b16 v[20:21], v16 offset:672
	s_waitcnt lgkmcnt(0)
	v_mfma_f32_16x16x32_bf16 v[4:7], v[4:7], v[18:21], 0
	ds_read_b64_tr_b16 v[18:19], v16 offset:4704
	ds_read_b64_tr_b16 v[20:21], v16 offset:5280
	v_lshl_add_u64 v[14:15], v[0:1], 0, v[14:15]
	v_lshl_add_u64 v[0:1], v[0:1], 0, v[2:3]
	s_waitcnt lgkmcnt(0)
	v_mfma_f32_16x16x32_bf16 v[4:7], v[8:11], v[18:21], v[4:7]
	s_nop 7
	v_cvt_pk_bf16_f32 v4, v4, v5
	v_cvt_pk_bf16_f32 v5, v6, v7
	v_lshl_add_u64 v[6:7], v[26:27], 0, v[2:3]
	flat_store_dwordx2 v[6:7], v[4:5]
	ds_read_b64_tr_b16 v[4:5], v16 offset:9312
	ds_read_b64_tr_b16 v[6:7], v16 offset:9888
	ds_read_b64_tr_b16 v[8:9], v16 offset:13920
	ds_read_b64_tr_b16 v[10:11], v16 offset:14496
	ds_read_b64_tr_b16 v[18:19], v16
	ds_read_b64_tr_b16 v[20:21], v16 offset:576
	ds_read_b64_tr_b16 v[22:23], v16 offset:4608
	ds_read_b64_tr_b16 v[24:25], v16 offset:5184
	s_waitcnt lgkmcnt(0)
	v_mfma_f32_16x16x32_bf16 v[18:21], v[4:7], v[18:21], 0
	v_mfma_f32_16x16x32_bf16 v[18:21], v[8:11], v[22:25], v[18:21]
	s_nop 7
	v_cvt_pk_bf16_f32 v18, v18, v19
	v_cvt_pk_bf16_f32 v19, v20, v21
	flat_store_dwordx2 v[12:13], v[18:19] offset:96
	ds_read_b64_tr_b16 v[18:19], v16 offset:32
	ds_read_b64_tr_b16 v[20:21], v16 offset:608
	ds_read_b64_tr_b16 v[22:23], v16 offset:4640
	ds_read_b64_tr_b16 v[24:25], v16 offset:5216
	s_waitcnt lgkmcnt(0)
	v_mfma_f32_16x16x32_bf16 v[18:21], v[4:7], v[18:21], 0
	v_mfma_f32_16x16x32_bf16 v[18:21], v[8:11], v[22:25], v[18:21]
	s_nop 7
	v_cvt_pk_bf16_f32 v18, v18, v19
	v_cvt_pk_bf16_f32 v19, v20, v21
	flat_store_dwordx2 v[12:13], v[18:19] offset:2144
	ds_read_b64_tr_b16 v[18:19], v16 offset:64
	ds_read_b64_tr_b16 v[20:21], v16 offset:640
	ds_read_b64_tr_b16 v[22:23], v16 offset:4672
	ds_read_b64_tr_b16 v[24:25], v16 offset:5248
	s_waitcnt lgkmcnt(0)
	v_mfma_f32_16x16x32_bf16 v[18:21], v[4:7], v[18:21], 0
	v_mfma_f32_16x16x32_bf16 v[18:21], v[8:11], v[22:25], v[18:21]
	s_nop 7
	v_cvt_pk_bf16_f32 v12, v18, v19
	v_cvt_pk_bf16_f32 v13, v20, v21
	flat_store_dwordx2 v[14:15], v[12:13]
	ds_read_b64_tr_b16 v[12:13], v16 offset:96
	ds_read_b64_tr_b16 v[14:15], v16 offset:672
	s_waitcnt lgkmcnt(0)
	v_mfma_f32_16x16x32_bf16 v[4:7], v[4:7], v[12:15], 0
	ds_read_b64_tr_b16 v[12:13], v16 offset:4704
	ds_read_b64_tr_b16 v[14:15], v16 offset:5280
	s_waitcnt lgkmcnt(0)
	v_mfma_f32_16x16x32_bf16 v[4:7], v[8:11], v[12:15], v[4:7]
	s_nop 7
	v_cvt_pk_bf16_f32 v4, v4, v5
	v_cvt_pk_bf16_f32 v5, v6, v7
	flat_store_dwordx2 v[0:1], v[4:5]
	s_waitcnt lgkmcnt(0)
	s_branch .LBB0_515
